# DN step B: decay/beta LDS reads hoisted into 2 b128 reads per tile (8 serialized LDS round trips removed per tile); plus MODE2/4 epilogues rewritten with batched prefetched x loads; MODE3 conv weights
# speedup vs baseline: 1.0103x; 1.0026x over previous
.LBB0_649:
	s_and_b32 s0, s60, 1
	s_add_i32 s64, 16, 0x1c800
	v_mov_b32_e32 v71, v120
	v_mov_b32_e32 v0, v107
	v_mov_b32_e32 v1, v121
	s_cmp_eq_u32 s0, 0
	s_cselect_b64 s[14:15], -1, 0
	v_add_u32_e32 v0, s33, v71
	v_lshlrev_b32_e32 v60, 4, v1
	s_and_b64 s[0:1], s[14:15], exec
	v_mul_lo_u32 v3, v0, s21
	v_add_u32_e32 v0, 16, v60
	s_cselect_b32 s66, 16, s54
	v_add_u32_e32 v69, v0, v3
	v_add_u32_e32 v80, s35, v71
	v_add3_u32 v70, s66, v3, v60
	v_mad_u64_u32 v[86:87], s[0:1], v80, s21, v[0:1]
	ds_read_b128 v[60:63], v69 offset:17408
	ds_read_b128 v[64:67], v70
	ds_read_b128 v[72:75], v86 offset:17408
	s_waitcnt lgkmcnt(0)
	v_mfma_f32_16x16x32_bf16 v[60:63], v[60:63], v[72:75], 0
	s_cselect_b32 s65, s64, s55
	v_lshl_add_u32 v68, v1, 2, s33
	v_lshl_add_u32 v1, v80, 2, s65
	v_mfma_f32_16x16x32_bf16 v[64:67], v[64:67], v[72:75], 0
	ds_read_b128 v[72:75], v69 offset:17472
	ds_read_b128 v[76:79], v70 offset:64
	ds_read_b128 v[82:85], v86 offset:17472
	v_cmp_ge_i32_e64 s[12:13], v68, v80
	s_waitcnt lgkmcnt(0)
	v_mfma_f32_16x16x32_bf16 v[60:63], v[72:75], v[82:85], v[60:63]
	v_mfma_f32_16x16x32_bf16 v[64:67], v[76:79], v[82:85], v[64:67]
	ds_read_b128 v[72:75], v69 offset:17536
	ds_read_b128 v[76:79], v70 offset:128
	ds_read_b128 v[82:85], v86 offset:17536
	s_waitcnt lgkmcnt(0)
	v_mfma_f32_16x16x32_bf16 v[60:63], v[72:75], v[82:85], v[60:63]
	v_mfma_f32_16x16x32_bf16 v[72:75], v[76:79], v[82:85], v[64:67]
	s_nop 2
	ds_read_b128 v[64:67], v69 offset:17600
	ds_read_b128 v[76:79], v70 offset:192
	ds_read_b128 v[82:85], v86 offset:17600
	ds_read_b32 v81, v1
	v_lshl_add_u32 v1, v68, 2, s65
	ds_read_b128 v[160:163], v1
	ds_read_b128 v[164:167], v1 offset:256
	s_waitcnt lgkmcnt(3)
	v_mfma_f32_16x16x32_bf16 v[64:67], v[64:67], v[82:85], v[60:63]
	v_mfma_f32_16x16x32_bf16 v[60:63], v[76:79], v[82:85], v[72:75]
	s_nop 2
	v_mov_b32_e32 v72, 0
	v_mov_b32_e32 v73, 0
	s_waitcnt lgkmcnt(0)
	s_and_saveexec_b64 s[0:1], s[12:13]
	s_cbranch_execz .LBB0_651
	v_mov_b32_e32 v3, v160
	s_nop 0
	v_sub_f32_e32 v3, v3, v81
	v_mul_f32_e32 v3, 0x3fb8aa3b, v3
	v_exp_f32_e32 v73, v3
.LBB0_651:
	s_or_b64 exec, exec, s[0:1]
	s_and_b64 s[0:1], s[14:15], exec
	s_mov_b32 s0, 0x25900
	s_cselect_b32 s0, 0x1c900, s0
	s_add_i32 s0, s0, 16
	v_cmp_gt_i32_e32 vcc, v68, v80
	v_lshl_add_u32 v3, v68, 2, s0
	s_and_saveexec_b64 s[0:1], vcc
	s_cbranch_execz .LBB0_653
	v_mov_b32_e32 v72, v164
	s_nop 0
	v_mul_f32_e32 v64, v64, v72
	v_mul_f32_e32 v72, v73, v64

.LBB0_655:
	v_mul_f32_e32 v60, v60, v73
	v_cvt_pk_bf16_f32 v60, v60, s0
	v_add_u32_e32 v72, 0x19200, v75
	v_or_b32_e32 v76, 1, v68
	ds_write_b16 v72, v60
	v_cmp_ge_i32_e32 vcc, v76, v80
	v_mov_b32_e32 v72, 0
	v_mov_b32_e32 v60, 0
	s_and_saveexec_b64 s[18:19], vcc
	s_cbranch_execz .LBB0_657
	v_mov_b32_e32 v60, v161
	s_nop 0
	v_sub_f32_e32 v60, v60, v81
	v_mul_f32_e32 v60, 0x3fb8aa3b, v60
	v_exp_f32_e32 v60, v60
.LBB0_657:
	s_or_b64 exec, exec, s[18:19]
	s_and_saveexec_b64 s[18:19], s[12:13]
	s_cbranch_execz .LBB0_659
	v_mov_b32_e32 v72, v165
	s_nop 0
	v_mul_f32_e32 v65, v65, v72
	v_mul_f32_e32 v72, v60, v65

.LBB0_661:
	v_mul_f32_e32 v60, v61, v60
	v_cvt_pk_bf16_f32 v60, v60, s0
	v_add_u32_e32 v61, 0x19200, v65
	v_or_b32_e32 v72, 2, v68
	ds_write_b16 v61, v60
	v_cmp_ge_i32_e32 vcc, v72, v80
	v_mov_b32_e32 v61, 0
	v_mov_b32_e32 v60, 0
	s_and_saveexec_b64 s[12:13], vcc
	s_cbranch_execz .LBB0_663
	v_mov_b32_e32 v60, v162
	s_nop 0
	v_sub_f32_e32 v60, v60, v81
	v_mul_f32_e32 v60, 0x3fb8aa3b, v60
	v_exp_f32_e32 v60, v60
.LBB0_663:
	s_or_b64 exec, exec, s[12:13]
	v_cmp_gt_i32_e32 vcc, v72, v80
	s_and_saveexec_b64 s[12:13], vcc
	s_cbranch_execz .LBB0_665
	v_mov_b32_e32 v61, v166
	s_nop 0
	v_mul_f32_e32 v61, v66, v61
	v_mul_f32_e32 v61, v60, v61

.LBB0_667:
	v_mul_f32_e32 v60, v62, v60
	v_cvt_pk_bf16_f32 v60, v60, s0
	v_add_u32_e32 v61, 0x19200, v65
	v_or_b32_e32 v73, 3, v68
	ds_write_b16 v61, v60
	v_cmp_ge_i32_e32 vcc, v73, v80
	v_mov_b32_e32 v60, 0
	v_mov_b32_e32 v61, 0
	s_and_saveexec_b64 s[0:1], vcc
	s_cbranch_execz .LBB0_669
	v_mov_b32_e32 v61, v163
	s_nop 0
	v_sub_f32_e32 v61, v61, v81
	v_mul_f32_e32 v61, 0x3fb8aa3b, v61
	v_exp_f32_e32 v61, v61
.LBB0_669:
	s_or_b64 exec, exec, s[0:1]
	v_cmp_gt_i32_e32 vcc, v73, v80
	s_and_saveexec_b64 s[0:1], vcc
	s_cbranch_execz .LBB0_671
	v_mov_b32_e32 v60, v167
	s_nop 0
	v_mul_f32_e32 v60, v67, v60
	v_mul_f32_e32 v60, v61, v60

.LBB0_677:
	ds_read_b128 v[160:163], v1
	ds_read_b128 v[164:167], v1 offset:256
	v_add_u32_e32 v71, s63, v71
	v_mad_u64_u32 v[96:97], s[0:1], v71, s21, v[0:1]
	ds_read_b128 v[60:63], v69 offset:17408
	ds_read_b128 v[64:67], v70
	ds_read_b128 v[84:87], v96 offset:17408
	v_lshl_add_u32 v0, v71, 2, s65
	v_cmp_ge_i32_e64 s[12:13], v68, v71
	s_waitcnt lgkmcnt(0)
	v_mfma_f32_16x16x32_bf16 v[60:63], v[60:63], v[84:87], 0
	v_mfma_f32_16x16x32_bf16 v[64:67], v[64:67], v[84:87], 0
	ds_read_b128 v[84:87], v69 offset:17472
	ds_read_b128 v[88:91], v70 offset:64
	ds_read_b128 v[92:95], v96 offset:17472
	s_waitcnt lgkmcnt(0)
	v_mfma_f32_16x16x32_bf16 v[60:63], v[84:87], v[92:95], v[60:63]
	v_mfma_f32_16x16x32_bf16 v[64:67], v[88:91], v[92:95], v[64:67]
	ds_read_b128 v[84:87], v69 offset:17536
	ds_read_b128 v[88:91], v70 offset:128
	ds_read_b128 v[92:95], v96 offset:17536
	s_waitcnt lgkmcnt(0)
	v_mfma_f32_16x16x32_bf16 v[60:63], v[84:87], v[92:95], v[60:63]
	v_mfma_f32_16x16x32_bf16 v[84:87], v[88:91], v[92:95], v[64:67]
	s_nop 2
	ds_read_b128 v[64:67], v69 offset:17600
	ds_read_b128 v[88:91], v70 offset:192
	ds_read_b128 v[92:95], v96 offset:17600
	ds_read_b32 v0, v0
	v_mov_b32_e32 v70, 0
	s_waitcnt lgkmcnt(1)
	v_mfma_f32_16x16x32_bf16 v[64:67], v[64:67], v[92:95], v[60:63]
	v_mov_b32_e32 v69, 0
	v_mfma_f32_16x16x32_bf16 v[60:63], v[88:91], v[92:95], v[84:87]
	s_waitcnt lgkmcnt(0)
	s_and_saveexec_b64 s[0:1], s[12:13]
	s_cbranch_execz .LBB0_679
	v_mov_b32_e32 v69, v160
	s_nop 0
	v_sub_f32_e32 v69, v69, v0
	v_mul_f32_e32 v69, 0x3fb8aa3b, v69
	v_exp_f32_e32 v69, v69
.LBB0_679:
	s_or_b64 exec, exec, s[0:1]
	v_cmp_gt_i32_e32 vcc, v68, v71
	s_and_saveexec_b64 s[0:1], vcc
	s_cbranch_execz .LBB0_681
	v_mov_b32_e32 v68, v164
	s_nop 0
	v_mul_f32_e32 v64, v64, v68
	v_mul_f32_e32 v70, v69, v64

.LBB0_683:
	v_mul_f32_e32 v60, v60, v69
	v_cvt_pk_bf16_f32 v60, v60, s0
	v_add_u32_e32 v64, 0x19200, v64
	ds_write_b16 v64, v60
	v_cmp_ge_i32_e32 vcc, v76, v71
	v_mov_b32_e32 v64, 0
	v_mov_b32_e32 v60, 0
	s_and_saveexec_b64 s[18:19], vcc
	s_cbranch_execz .LBB0_685
	v_mov_b32_e32 v60, v161
	s_nop 0
	v_sub_f32_e32 v60, v60, v0
	v_mul_f32_e32 v60, 0x3fb8aa3b, v60
	v_exp_f32_e32 v60, v60
.LBB0_685:
	s_or_b64 exec, exec, s[18:19]
	s_and_saveexec_b64 s[18:19], s[12:13]
	s_cbranch_execz .LBB0_687
	v_mov_b32_e32 v64, v165
	s_nop 0
	v_mul_f32_e32 v64, v65, v64
	v_mul_f32_e32 v64, v60, v64

.LBB0_689:
	v_mul_f32_e32 v60, v61, v60
	v_cvt_pk_bf16_f32 v60, v60, s0
	v_add_u32_e32 v61, 0x19200, v65
	ds_write_b16 v61, v60
	v_cmp_ge_i32_e32 vcc, v72, v71
	v_mov_b32_e32 v61, 0
	v_mov_b32_e32 v60, 0
	s_and_saveexec_b64 s[12:13], vcc
	s_cbranch_execz .LBB0_691
	v_mov_b32_e32 v60, v162
	s_nop 0
	v_sub_f32_e32 v60, v60, v0
	v_mul_f32_e32 v60, 0x3fb8aa3b, v60
	v_exp_f32_e32 v60, v60
.LBB0_691:
	s_or_b64 exec, exec, s[12:13]
	v_cmp_gt_i32_e32 vcc, v72, v71
	s_and_saveexec_b64 s[12:13], vcc
	s_cbranch_execz .LBB0_693
	v_mov_b32_e32 v61, v166
	s_nop 0
	v_mul_f32_e32 v61, v66, v61
	v_mul_f32_e32 v61, v60, v61

.LBB0_695:
	v_mul_f32_e32 v60, v62, v60
	v_cvt_pk_bf16_f32 v60, v60, s0
	v_add_u32_e32 v61, 0x19200, v64
	ds_write_b16 v61, v60
	v_cmp_ge_i32_e32 vcc, v73, v71
	v_mov_b32_e32 v60, 0
	v_mov_b32_e32 v61, 0
	s_and_saveexec_b64 s[0:1], vcc
	s_cbranch_execz .LBB0_697
	v_mov_b32_e32 v1, v163
	s_nop 0
	v_sub_f32_e32 v0, v1, v0
	v_mul_f32_e32 v0, 0x3fb8aa3b, v0
	v_exp_f32_e32 v61, v0
.LBB0_697:
	s_or_b64 exec, exec, s[0:1]
	v_cmp_gt_i32_e32 vcc, v73, v71
	s_and_saveexec_b64 s[0:1], vcc
	s_cbranch_execz .LBB0_699
	s_waitcnt lgkmcnt(6)
	v_mov_b32_e32 v0, v167
	s_nop 0
	v_mul_f32_e32 v0, v67, v0
	v_mul_f32_e32 v60, v61, v0
